# A/B: attention phases without the static priority raise for waves 4-7 (on top of v36)
# speedup vs baseline: 1.0046x; 1.0046x over previous
; template <int KIND> ...
;     ...
;     if (wid >= 4) __builtin_amdgcn_s_setprio(1);
; __global__ void __launch_bounds__(NTHREADS, 2) mega_fwd(Args a_unused) {
;     ...
;                 const bool do_ctx = L < 3;
;                 if (kind == 0) { if (EN & 32) attn_phase<0>(lds, QKV, 3072, OB, a->in[10] + (size_t)(L / 3) * 16 * 465, nullptr, nullptr, 0.f, do_ctx, tid, wid, lane); }
;                 else if (kind == 1) { if (EN & 64) attn_phase<1>(lds, QKV, 1536, OB, nullptr, nullptr, nullptr, 0.f, do_ctx, tid, wid, lane); }
;                 else { if (EN & 128) attn_phase<2>(lds, QKV, 3072, OB, nullptr, a->in[17], a->in[18], a->lam_init, do_ctx, tid, wid, lane); }
.LBB0_93:
	v_readlane_b32 s2, v254, 63
	s_cmp_lt_i32 s2, 32
	v_readlane_b32 s2, v255, 2
	s_cselect_b64 s[6:7], -1, 0
	s_mov_b64 s[10:11], -1
	s_mov_b64 s[8:9], 0
	s_cmp_lt_i32 s2, 1
	s_mov_b64 s[4:5], 0
	s_cbranch_scc1 .LBB0_118
	v_readlane_b32 s2, v255, 2
	s_cmp_eq_u32 s2, 1
	s_mov_b64 s[4:5], -1
	s_cbranch_scc0 .LBB0_172
	s_cmp_lt_i32 s38, 4
	s_cbranch_scc1 .LBB0_97
	s_setprio 0

; template <int KIND> ...
;     ...
;     if (wid >= 4) __builtin_amdgcn_s_setprio(1);
; __global__ void __launch_bounds__(NTHREADS, 2) mega_fwd(Args a_unused) {
;     ...
;                 if (kind == 0) { if (EN & 32) attn_phase<0>(lds, QKV, 3072, OB, a->in[10] + (size_t)(L / 3) * 16 * 465, nullptr, nullptr, 0.f, do_ctx, tid, wid, lane); }
.LBB0_120:
	s_and_b64 vcc, exec, s[8:9]
	s_cbranch_vccz .LBB0_203
	s_load_dwordx2 s[4:5], s[0:1], 0x50
	s_cmp_lt_i32 s38, 4
	s_cbranch_scc1 .LBB0_123
	s_setprio 0

; template <int KIND> ...
;     ...
;     if (KIND == 2) { const float s01 = wave_sum(lam[lane] * lam[64 + lane]), s23 = wave_sum(lam[128 + lane] * lam[192 + lane]);
;         lam_full = __builtin_amdgcn_exp2f(s01 * LOG2E) - __builtin_amdgcn_exp2f(s23 * LOG2E) + lam_init; }
;     if (wid >= 4) __builtin_amdgcn_s_setprio(1);
.LBB0_174:
	s_load_dwordx4 s[8:11], s[0:1], 0x88
	s_load_dword s19, s[0:1], 0xb8
	v_ashrrev_i32_e32 v197, 31, v196
	v_cmp_lt_i32_e32 vcc, v226, v217
	s_cmp_gt_i32 s38, 3
	s_waitcnt lgkmcnt(0)
	v_mov_b32_e32 v0, s8
	v_mov_b32_e32 v1, s9
	v_lshl_add_u64 v[2:3], v[196:197], 2, v[0:1]
	global_load_dword v0, v[2:3], off
	global_load_dword v1, v[2:3], off offset:256
	global_load_dword v9, v[2:3], off offset:512
	s_nop 0
	global_load_dword v2, v[2:3], off offset:768
	v_cndmask_b32_e32 v5, v216, v226, vcc
	v_lshlrev_b32_e32 v5, 2, v5
	v_cmp_lt_i32_e32 vcc, v246, v217
	s_cselect_b64 s[8:9], -1, 0
	s_cmp_lt_i32 s38, 4
	s_waitcnt vmcnt(0)
	v_mul_f32_e32 v4, v0, v1
	ds_bpermute_b32 v4, v5, v4
	s_waitcnt vmcnt(0)
	v_mul_f32_e32 v3, v9, v2
	ds_bpermute_b32 v3, v5, v3
	s_waitcnt lgkmcnt(1)
	v_fmac_f32_e32 v4, v0, v1
	v_cndmask_b32_e32 v0, v216, v246, vcc
	v_lshlrev_b32_e32 v6, 2, v0
	ds_bpermute_b32 v0, v6, v4
	v_cmp_lt_i32_e32 vcc, v247, v217
	s_waitcnt lgkmcnt(1)
	v_fmac_f32_e32 v3, v9, v2
	ds_bpermute_b32 v2, v6, v3
	v_cndmask_b32_e32 v1, v216, v247, vcc
	s_waitcnt lgkmcnt(1)
	v_add_f32_e32 v0, v4, v0
	v_lshlrev_b32_e32 v4, 2, v1
	ds_bpermute_b32 v1, v4, v0
	s_waitcnt lgkmcnt(1)
	v_add_f32_e32 v2, v3, v2
	ds_bpermute_b32 v3, v4, v2
	s_waitcnt lgkmcnt(1)
	v_add_f32_e32 v0, v0, v1
	v_xor_b32_e32 v1, 8, v216
	v_cmp_lt_i32_e32 vcc, v1, v217
	s_waitcnt lgkmcnt(0)
	v_add_f32_e32 v2, v2, v3
	v_cndmask_b32_e32 v1, v216, v1, vcc
	v_lshlrev_b32_e32 v7, 2, v1
	ds_bpermute_b32 v1, v7, v0
	ds_bpermute_b32 v3, v7, v2
	v_cmp_lt_i32_e32 vcc, v222, v217
	s_waitcnt lgkmcnt(1)
	v_add_f32_e32 v0, v0, v1
	v_cndmask_b32_e32 v1, v216, v222, vcc
	v_lshlrev_b32_e32 v8, 2, v1
	ds_bpermute_b32 v1, v8, v0
	s_waitcnt lgkmcnt(1)
	v_add_f32_e32 v2, v2, v3
	ds_bpermute_b32 v3, v8, v2
	v_cmp_lt_i32_e32 vcc, v223, v217
	s_waitcnt lgkmcnt(1)
	v_add_f32_e32 v0, v0, v1
	v_cndmask_b32_e32 v1, v216, v223, vcc
	v_lshlrev_b32_e32 v197, 2, v1
	s_waitcnt lgkmcnt(0)
	v_add_f32_e32 v2, v2, v3
	ds_bpermute_b32 v1, v197, v0
	ds_bpermute_b32 v3, v197, v2
	s_cbranch_scc1 .LBB0_176
	s_setprio 0
